# gather: per-task softmax denominator reduced with v_permlane16/32_swap and broadcast by v_readlane instead of six ds_bpermute round trips
# speedup vs baseline: 1.0019x; 1.0004x over previous
.LBB0_978:
	s_abs_i32 s10, s70
	s_mul_hi_u32 s12, s10, s56
	s_mul_i32 s14, s12, s45
	s_ashr_i32 s8, s70, 31
	s_sub_i32 s10, s10, s14
	s_andn2_b32 s13, 0x200, s69
	s_xor_b32 s8, s8, s55
	s_add_i32 s14, s12, 1
	s_sub_i32 s15, s10, s45
	s_cmp_ge_u32 s10, s45
	s_cselect_b32 s12, s14, s12
	s_cselect_b32 s10, s15, s10
	s_add_i32 s14, s12, 1
	s_cmp_ge_u32 s10, s45
	s_cselect_b32 s10, s14, s12
	s_xor_b32 s10, s10, s8
	s_sub_i32 s12, s10, s8
	s_lshl_b32 s8, s12, s24
	s_mul_i32 s12, s57, s12
	s_add_i32 s12, s70, s12
	s_add_i32 s8, s8, s41
	s_mul_i32 s12, s12, s25
	s_mov_b32 s11, s70
	s_ashr_i32 s10, s8, 2
	s_and_b32 s8, s8, 3
	s_add_i32 s12, s12, s40
	s_add_i32 s70, s70, 1
	s_cmp_lt_i32 s70, s43
	s_cselect_b32 s33, s70, s11
	s_abs_i32 s14, s33
	s_mul_hi_u32 s15, s14, s56
	s_mul_i32 s16, s15, s45
	s_ashr_i32 s11, s33, 31
	s_sub_i32 s14, s14, s16
	s_xor_b32 s11, s11, s55
	s_add_i32 s16, s15, 1
	s_sub_i32 s17, s14, s45
	s_cmp_ge_u32 s14, s45
	s_cselect_b32 s15, s16, s15
	s_cselect_b32 s14, s17, s14
	s_add_i32 s16, s15, 1
	s_cmp_ge_u32 s14, s45
	s_cselect_b32 s14, s16, s15
	s_xor_b32 s14, s14, s11
	s_sub_i32 s71, s14, s11
	s_lshl_b32 s11, s71, s24
	s_add_i32 s11, s11, s41
	s_ashr_i32 s72, s11, 2
	s_and_b32 s82, s11, 3
	s_ashr_i32 s11, s10, 31
	s_lshl_b64 s[14:15], s[10:11], 22
	s_add_u32 s22, s80, s14
	s_addc_u32 s23, s81, s15
	s_ashr_i32 s73, s72, 31
	s_lshl_b64 s[16:17], s[72:73], 22
	s_add_u32 s74, s80, s16
	s_addc_u32 s75, s81, s17
	s_add_i32 s83, s47, s13
	s_add_u32 s13, s37, s14
	s_addc_u32 s14, s79, s15
	s_lshl_b32 s15, s8, 7
	s_add_u32 s18, s13, s15
	s_addc_u32 s19, s14, 0
	s_add_u32 s22, s22, s15
	s_addc_u32 s23, s23, 0
	s_add_u32 s13, s37, s16
	s_addc_u32 s15, s79, s17
	s_lshl_b32 s16, s82, 7
	s_add_u32 s14, s13, s16
	s_addc_u32 s15, s15, 0
	s_add_u32 s16, s74, s16
	s_mul_i32 s71, s71, s42
	s_addc_u32 s17, s75, 0
	s_sub_i32 s33, s33, s71
	s_mul_i32 s33, s33, s25
	s_add_i32 s33, s33, s40
	s_min_i32 s13, s12, 0xff
	s_lshl_b64 s[72:73], s[72:73], 13
	s_ashr_i32 s71, s33, 31
	s_add_u32 s72, s72, s33
	s_addc_u32 s73, s73, s71
	s_mul_i32 s71, s73, 0x1200
	s_mul_hi_u32 s74, s72, 0x1200
	s_add_i32 s71, s74, s71
	s_mul_i32 s74, s72, 0x1200
	s_add_u32 s74, s38, s74
	s_addc_u32 s75, s39, s71
	s_waitcnt lgkmcnt(0)
	v_lshl_or_b32 v42, s82, 9, v62
	v_lshlrev_b32_e32 v34, 9, v32
	v_lshl_add_u64 v[14:15], s[74:75], 0, v[42:43]
	s_cmpk_gt_i32 s33, 0xff
	v_and_b32_e32 v42, 0x1fffe00, v34
	v_mov_b32_e32 v57, v43
	s_cselect_b64 vcc, -1, 0
	s_lshl_b64 s[72:73], s[72:73], 9
	v_lshl_add_u64 v[34:35], s[18:19], 0, v[42:43]
	s_mov_b32 m0, s44
	v_lshl_add_u64 v[14:15], v[14:15], 0, v[56:57]
	v_lshl_add_u64 v[16:17], v[54:55], 0, s[72:73]
	v_lshl_add_u64 v[34:35], v[34:35], 0, v[44:45]
	global_load_dwordx2 v[30:31], v[16:17], off
	global_load_dwordx4 v[18:21], v[14:15], off
	s_nop 0
	global_load_dwordx4 v[14:17], v[14:15], off offset:64
	s_nop 0
	global_load_lds_dwordx4 v[34:35], off
	v_lshl_add_u64 v[34:35], s[22:23], 0, v[42:43]
	v_lshl_add_u64 v[34:35], v[34:35], 0, v[52:53]
	s_mov_b32 m0, s58
	v_lshlrev_b32_sdwa v42, v64, v32 dst_sel:DWORD dst_unused:UNUSED_PAD src0_sel:DWORD src1_sel:WORD_1
	global_load_lds_dwordx4 v[34:35], off
	v_lshl_add_u64 v[34:35], s[18:19], 0, v[42:43]
	v_lshl_add_u64 v[34:35], v[34:35], 0, v[50:51]
	s_mov_b32 m0, s59
	v_lshlrev_b32_e32 v32, 9, v33
	global_load_lds_dwordx4 v[34:35], off
	v_lshl_add_u64 v[34:35], s[22:23], 0, v[42:43]
	v_lshl_add_u64 v[34:35], v[34:35], 0, v[52:53]
	s_mov_b32 m0, s60
	v_and_b32_e32 v42, 0x1fffe00, v32
	global_load_lds_dwordx4 v[34:35], off
	v_lshl_add_u64 v[34:35], s[18:19], 0, v[42:43]
	v_lshl_add_u64 v[34:35], v[34:35], 0, v[48:49]
	s_mov_b32 m0, s61
	s_nop 0
	global_load_lds_dwordx4 v[34:35], off
	v_lshl_add_u64 v[34:35], s[22:23], 0, v[42:43]
	v_lshlrev_b32_sdwa v42, v64, v33 dst_sel:DWORD dst_unused:UNUSED_PAD src0_sel:DWORD src1_sel:WORD_1
	v_lshl_add_u64 v[34:35], v[34:35], 0, v[52:53]
	s_mov_b32 m0, s64
	v_lshl_add_u64 v[32:33], s[18:19], 0, v[42:43]
	global_load_lds_dwordx4 v[34:35], off
	v_lshl_add_u64 v[32:33], v[32:33], 0, v[46:47]
	s_mov_b32 m0, s65
	s_nop 0
	global_load_lds_dwordx4 v[32:33], off
	v_lshl_add_u64 v[32:33], s[22:23], 0, v[42:43]
	v_lshl_add_u64 v[32:33], v[32:33], 0, v[52:53]
	s_mov_b32 m0, s66
	s_nop 0
	global_load_lds_dwordx4 v[32:33], off
	s_waitcnt vmcnt(8)
	ds_read_b128 v[36:39], v145
	ds_read_b128 v[162:165], v149
	ds_read_b128 v[166:169], v151
	ds_read_b128 v[170:173], v153
	s_waitcnt lgkmcnt(0)
	v_mov_b64_e32 v[34:35], v[28:29]
	v_mov_b64_e32 v[32:33], v[26:27]
	v_add_u32_e32 v28, s83, v63
	v_lshl_add_u32 v29, v1, 1, s83
	s_waitcnt vmcnt(0)
	v_cndmask_b32_e32 v26, v60, v30, vcc
	v_cndmask_b32_e32 v27, v61, v31, vcc
	v_mfma_f32_16x16x32_bf16 v[36:39], v[36:39], v[10:13], 0
	v_cmp_ge_i32_e32 vcc, s13, v65
	s_mov_b32 m0, s46
	v_mfma_f32_16x16x32_bf16 v[36:39], v[162:165], v[6:9], v[36:39]
	v_mfma_f32_16x16x32_bf16 v[162:165], v[166:169], v[10:13], 0
	v_mfma_f32_16x16x32_bf16 v[162:165], v[170:173], v[6:9], v[162:165]
	s_nop 5
	v_mul_f32_e32 v30, 0x3fb8aa3b, v36
	v_exp_f32_e32 v30, v30
	s_nop 0
	v_cndmask_b32_e32 v40, 0, v30, vcc
	v_mul_f32_e32 v30, 0x3fb8aa3b, v37
	v_mul_f32_e32 v31, 0x3fb8aa3b, v162
	v_exp_f32_e32 v31, v31
	v_cmp_ge_i32_e32 vcc, s13, v66
	v_exp_f32_e32 v30, v30
	s_nop 0
	v_cndmask_b32_e32 v41, 0, v31, vcc
	v_mul_f32_e32 v31, 0x3fb8aa3b, v163
	v_exp_f32_e32 v31, v31
	v_cmp_ge_i32_e32 vcc, s13, v67
	s_nop 1
	v_cndmask_b32_e32 v57, 0, v30, vcc
	v_mul_f32_e32 v30, 0x3fb8aa3b, v38
	v_cmp_ge_i32_e32 vcc, s13, v68
	v_exp_f32_e32 v30, v30
	v_cvt_pk_bf16_f32 v36, v40, v57
	s_nop 0
	v_cndmask_b32_e32 v59, 0, v31, vcc
	v_mul_f32_e32 v31, 0x3fb8aa3b, v164
	v_exp_f32_e32 v31, v31
	v_cmp_ge_i32_e32 vcc, s13, v69
	s_nop 1
	v_cndmask_b32_e32 v155, 0, v30, vcc
	v_mul_f32_e32 v30, 0x3fb8aa3b, v39
	v_cmp_ge_i32_e32 vcc, s13, v70
	v_exp_f32_e32 v30, v30
	s_nop 0
	v_cndmask_b32_e32 v156, 0, v31, vcc
	v_mul_f32_e32 v31, 0x3fb8aa3b, v165
	v_exp_f32_e32 v31, v31
	v_cmp_ge_i32_e32 vcc, s13, v71
	s_nop 1
	v_cndmask_b32_e32 v157, 0, v30, vcc
	v_lshlrev_b32_e32 v30, 9, v22
	v_cmp_ge_i32_e32 vcc, s13, v72
	v_and_b32_e32 v42, 0x1fffe00, v30
	v_cvt_pk_bf16_f32 v37, v155, v157
	v_cvt_pk_bf16_f32 v38, v41, v59
	s_nop 0
	v_cndmask_b32_e32 v158, 0, v31, vcc
	v_lshl_add_u64 v[30:31], s[18:19], 0, v[42:43]
	v_cvt_pk_bf16_f32 v39, v156, v158
	ds_read_b64_tr_b16 v[174:175], v73
	ds_read_b64_tr_b16 v[176:177], v74
	ds_read_b64_tr_b16 v[170:171], v75
	ds_read_b64_tr_b16 v[172:173], v76
	ds_read_b64_tr_b16 v[166:167], v77
	ds_read_b64_tr_b16 v[168:169], v78
	ds_read_b64_tr_b16 v[162:163], v79
	ds_read_b64_tr_b16 v[164:165], v80
	s_waitcnt lgkmcnt(0)
	v_lshl_add_u64 v[30:31], v[30:31], 0, v[44:45]
	global_load_lds_dwordx4 v[30:31], off
	v_lshl_add_u64 v[30:31], s[22:23], 0, v[42:43]
	v_lshl_add_u64 v[30:31], v[30:31], 0, v[52:53]
	s_mov_b32 m0, s48
	v_lshlrev_b32_sdwa v42, v64, v22 dst_sel:DWORD dst_unused:UNUSED_PAD src0_sel:DWORD src1_sel:WORD_1
	global_load_lds_dwordx4 v[30:31], off
	v_lshl_add_u64 v[30:31], s[18:19], 0, v[42:43]
	v_lshl_add_u64 v[30:31], v[30:31], 0, v[50:51]
	s_mov_b32 m0, s49
	v_lshlrev_b32_e32 v22, 9, v23
	global_load_lds_dwordx4 v[30:31], off
	v_lshl_add_u64 v[30:31], s[22:23], 0, v[42:43]
	v_lshl_add_u64 v[30:31], v[30:31], 0, v[52:53]
	s_mov_b32 m0, s50
	v_and_b32_e32 v42, 0x1fffe00, v22
	global_load_lds_dwordx4 v[30:31], off
	v_lshl_add_u64 v[30:31], s[18:19], 0, v[42:43]
	v_lshl_add_u64 v[30:31], v[30:31], 0, v[48:49]
	s_mov_b32 m0, s51
	v_mfma_f32_16x16x32_bf16 v[174:177], v[36:39], v[174:177], 0
	global_load_lds_dwordx4 v[30:31], off
	v_lshl_add_u64 v[30:31], s[22:23], 0, v[42:43]
	v_lshlrev_b32_sdwa v42, v64, v23 dst_sel:DWORD dst_unused:UNUSED_PAD src0_sel:DWORD src1_sel:WORD_1
	v_lshl_add_u64 v[30:31], v[30:31], 0, v[52:53]
	s_mov_b32 m0, s52
	v_lshl_add_u64 v[22:23], s[18:19], 0, v[42:43]
	global_load_lds_dwordx4 v[30:31], off
	v_lshl_add_u64 v[22:23], v[22:23], 0, v[46:47]
	s_mov_b32 m0, s53
	v_mfma_f32_16x16x32_bf16 v[170:173], v[36:39], v[170:173], 0
	global_load_lds_dwordx4 v[22:23], off
	v_lshl_add_u64 v[22:23], s[22:23], 0, v[42:43]
	v_lshl_add_u64 v[22:23], v[22:23], 0, v[52:53]
	s_mov_b32 m0, s54
	v_mfma_f32_16x16x32_bf16 v[166:169], v[36:39], v[166:169], 0
	global_load_lds_dwordx4 v[22:23], off
	s_waitcnt vmcnt(8)
	ds_read_b128 v[178:181], v145 offset:8192
	ds_read_b128 v[182:185], v149 offset:8192
	ds_read_b128 v[186:189], v151 offset:8192
	ds_read_b128 v[190:193], v153 offset:8192
	v_add_f32_e32 v22, v40, v41
	v_add_f32_e32 v22, 0, v22
	v_add_f32_e32 v23, v57, v59
	v_mfma_f32_16x16x32_bf16 v[36:39], v[36:39], v[162:165], 0
	v_add_f32_e32 v22, v23, v22
	v_add_f32_e32 v23, v155, v156
	v_add_f32_e32 v22, v23, v22
	v_add_f32_e32 v23, v157, v158
	v_add_f32_e32 v30, v23, v22
	s_waitcnt lgkmcnt(0)
	v_mfma_f32_16x16x32_bf16 v[162:165], v[178:181], v[10:13], 0
	v_cmp_ge_i32_e32 vcc, s13, v81
	s_mov_b32 m0, s44
	v_mfma_f32_16x16x32_bf16 v[178:181], v[186:189], v[10:13], 0
	v_mfma_f32_16x16x32_bf16 v[162:165], v[182:185], v[6:9], v[162:165]
	v_mfma_f32_16x16x32_bf16 v[178:181], v[190:193], v[6:9], v[178:181]
	s_nop 6
	v_mul_f32_e32 v22, 0x3fb8aa3b, v162
	v_exp_f32_e32 v22, v22
	v_mul_f32_e32 v23, 0x3fb8aa3b, v178
	v_exp_f32_e32 v23, v23
	v_cndmask_b32_e32 v31, 0, v22, vcc
	v_mul_f32_e32 v22, 0x3fb8aa3b, v163
	v_cmp_ge_i32_e32 vcc, s13, v82
	v_exp_f32_e32 v22, v22
	s_nop 0
	v_cndmask_b32_e32 v40, 0, v23, vcc
	v_mul_f32_e32 v23, 0x3fb8aa3b, v179
	v_exp_f32_e32 v23, v23
	v_cmp_ge_i32_e32 vcc, s13, v83
	s_nop 1
	v_cndmask_b32_e32 v41, 0, v22, vcc
	v_mul_f32_e32 v22, 0x3fb8aa3b, v164
	v_cmp_ge_i32_e32 vcc, s13, v84
	v_exp_f32_e32 v22, v22
	v_cvt_pk_bf16_f32 v162, v31, v41
	v_add_f32_e32 v31, v31, v40
	v_cndmask_b32_e32 v57, 0, v23, vcc
	v_mul_f32_e32 v23, 0x3fb8aa3b, v180
	v_exp_f32_e32 v23, v23
	v_cmp_ge_i32_e32 vcc, s13, v85
	v_add_f32_e32 v30, v30, v31
	v_add_f32_e32 v31, v41, v57
	v_cndmask_b32_e32 v59, 0, v22, vcc
	v_mul_f32_e32 v22, 0x3fb8aa3b, v165
	v_cmp_ge_i32_e32 vcc, s13, v86
	v_exp_f32_e32 v22, v22
	v_add_f32_e32 v30, v31, v30
	v_cndmask_b32_e32 v155, 0, v23, vcc
	v_mul_f32_e32 v23, 0x3fb8aa3b, v181
	v_exp_f32_e32 v23, v23
	v_cmp_ge_i32_e32 vcc, s13, v87
	v_add_f32_e32 v31, v59, v155
	v_add_f32_e32 v30, v31, v30
	v_cndmask_b32_e32 v156, 0, v22, vcc
	v_lshlrev_b32_e32 v22, 9, v24
	v_cmp_ge_i32_e32 vcc, s13, v88
	v_and_b32_e32 v42, 0x1fffe00, v22
	v_cvt_pk_bf16_f32 v163, v59, v156
	v_cvt_pk_bf16_f32 v164, v40, v57
	s_nop 0
	v_cndmask_b32_e32 v157, 0, v23, vcc
	v_lshl_add_u64 v[22:23], s[18:19], 0, v[42:43]
	v_cvt_pk_bf16_f32 v165, v155, v157
	ds_read_b64_tr_b16 v[190:191], v89
	ds_read_b64_tr_b16 v[192:193], v90
	ds_read_b64_tr_b16 v[186:187], v91
	ds_read_b64_tr_b16 v[188:189], v92
	ds_read_b64_tr_b16 v[182:183], v93
	ds_read_b64_tr_b16 v[184:185], v94
	ds_read_b64_tr_b16 v[178:179], v95
	ds_read_b64_tr_b16 v[180:181], v96
	s_waitcnt lgkmcnt(0)
	v_lshl_add_u64 v[22:23], v[22:23], 0, v[44:45]
	global_load_lds_dwordx4 v[22:23], off
	v_lshl_add_u64 v[22:23], s[22:23], 0, v[42:43]
	v_lshl_add_u64 v[22:23], v[22:23], 0, v[52:53]
	s_mov_b32 m0, s58
	v_lshlrev_b32_sdwa v42, v64, v24 dst_sel:DWORD dst_unused:UNUSED_PAD src0_sel:DWORD src1_sel:WORD_1
	global_load_lds_dwordx4 v[22:23], off
	v_lshl_add_u64 v[22:23], s[18:19], 0, v[42:43]
	v_lshl_add_u64 v[22:23], v[22:23], 0, v[50:51]
	s_mov_b32 m0, s59
	v_mfma_f32_16x16x32_bf16 v[170:173], v[162:165], v[186:189], v[170:173]
	global_load_lds_dwordx4 v[22:23], off
	v_lshl_add_u64 v[22:23], s[22:23], 0, v[42:43]
	v_lshl_add_u64 v[22:23], v[22:23], 0, v[52:53]
	s_mov_b32 m0, s60
	v_mfma_f32_16x16x32_bf16 v[166:169], v[162:165], v[182:185], v[166:169]
	global_load_lds_dwordx4 v[22:23], off
	v_lshlrev_b32_e32 v22, 9, v25
	v_and_b32_e32 v42, 0x1fffe00, v22
	v_lshl_add_u64 v[22:23], s[18:19], 0, v[42:43]
	v_lshl_add_u64 v[22:23], v[22:23], 0, v[48:49]
	s_mov_b32 m0, s61
	v_mfma_f32_16x16x32_bf16 v[36:39], v[162:165], v[178:181], v[36:39]
	global_load_lds_dwordx4 v[22:23], off
	v_lshl_add_u64 v[22:23], s[22:23], 0, v[42:43]
	v_lshl_add_u64 v[22:23], v[22:23], 0, v[52:53]
	s_mov_b32 m0, s64
	v_lshlrev_b32_sdwa v42, v64, v25 dst_sel:DWORD dst_unused:UNUSED_PAD src0_sel:DWORD src1_sel:WORD_1
	global_load_lds_dwordx4 v[22:23], off
	v_lshl_add_u64 v[22:23], s[18:19], 0, v[42:43]
	v_lshl_add_u64 v[22:23], v[22:23], 0, v[46:47]
	s_mov_b32 m0, s65
	v_add_f32_e32 v31, v156, v157
	global_load_lds_dwordx4 v[22:23], off
	v_lshl_add_u64 v[22:23], s[22:23], 0, v[42:43]
	v_lshl_add_u64 v[22:23], v[22:23], 0, v[52:53]
	s_mov_b32 m0, s66
	v_add_f32_e32 v40, v31, v30
	global_load_lds_dwordx4 v[22:23], off
	s_waitcnt vmcnt(8)
	v_mfma_f32_16x16x32_bf16 v[22:25], v[162:165], v[190:193], v[174:177]
	s_nop 2
	ds_read_b128 v[174:177], v145
	ds_read_b128 v[182:185], v149
	ds_read_b128 v[186:189], v151
	ds_read_b128 v[190:193], v153
	s_waitcnt lgkmcnt(0)
	v_mfma_f32_16x16x32_bf16 v[162:165], v[174:177], v[10:13], 0
	v_cmp_ge_i32_e32 vcc, s13, v97
	s_mov_b32 m0, s46
	v_mfma_f32_16x16x32_bf16 v[174:177], v[186:189], v[10:13], 0
	v_mfma_f32_16x16x32_bf16 v[162:165], v[182:185], v[6:9], v[162:165]
	v_mfma_f32_16x16x32_bf16 v[174:177], v[190:193], v[6:9], v[174:177]
	s_nop 6
	v_mul_f32_e32 v30, 0x3fb8aa3b, v162
	v_exp_f32_e32 v30, v30
	v_mul_f32_e32 v31, 0x3fb8aa3b, v174
	v_exp_f32_e32 v31, v31
	v_cndmask_b32_e32 v41, 0, v30, vcc
	v_mul_f32_e32 v30, 0x3fb8aa3b, v163
	v_cmp_ge_i32_e32 vcc, s13, v98
	v_exp_f32_e32 v30, v30
	s_nop 0
	v_cndmask_b32_e32 v57, 0, v31, vcc
	v_mul_f32_e32 v31, 0x3fb8aa3b, v175
	v_exp_f32_e32 v31, v31
	v_cmp_ge_i32_e32 vcc, s13, v99
	s_nop 1
	v_cndmask_b32_e32 v59, 0, v30, vcc
	v_mul_f32_e32 v30, 0x3fb8aa3b, v164
	v_cmp_ge_i32_e32 vcc, s13, v100
	v_exp_f32_e32 v30, v30
	v_cvt_pk_bf16_f32 v162, v41, v59
	s_nop 0
	v_cndmask_b32_e32 v155, 0, v31, vcc
	v_mul_f32_e32 v31, 0x3fb8aa3b, v176
	v_exp_f32_e32 v31, v31
	v_cmp_ge_i32_e32 vcc, s13, v101
	s_nop 1
	v_cndmask_b32_e32 v156, 0, v30, vcc
	v_mul_f32_e32 v30, 0x3fb8aa3b, v165
	v_cmp_ge_i32_e32 vcc, s13, v102
	v_exp_f32_e32 v30, v30
	s_nop 0
	v_cndmask_b32_e32 v157, 0, v31, vcc
	v_mul_f32_e32 v31, 0x3fb8aa3b, v177
	v_exp_f32_e32 v31, v31
	v_cmp_ge_i32_e32 vcc, s13, v103
	s_nop 1
	v_cndmask_b32_e32 v158, 0, v30, vcc
	v_lshlrev_b32_e32 v30, 9, v2
	v_cmp_ge_i32_e32 vcc, s13, v104
	v_and_b32_e32 v42, 0x1fffe00, v30
	v_cvt_pk_bf16_f32 v163, v156, v158
	v_cvt_pk_bf16_f32 v164, v57, v155
	s_nop 0
	v_cndmask_b32_e32 v160, 0, v31, vcc
	v_lshl_add_u64 v[30:31], s[18:19], 0, v[42:43]
	v_cvt_pk_bf16_f32 v165, v157, v160
	ds_read_b64_tr_b16 v[186:187], v73
	ds_read_b64_tr_b16 v[188:189], v74
	ds_read_b64_tr_b16 v[182:183], v75
	ds_read_b64_tr_b16 v[184:185], v76
	ds_read_b64_tr_b16 v[178:179], v77
	ds_read_b64_tr_b16 v[180:181], v78
	ds_read_b64_tr_b16 v[174:175], v79
	ds_read_b64_tr_b16 v[176:177], v80
	s_waitcnt lgkmcnt(0)
	v_lshl_add_u64 v[30:31], v[30:31], 0, v[44:45]
	global_load_lds_dwordx4 v[30:31], off
	v_lshl_add_u64 v[30:31], s[22:23], 0, v[42:43]
	v_lshl_add_u64 v[30:31], v[30:31], 0, v[52:53]
	s_mov_b32 m0, s48
	v_lshlrev_b32_sdwa v42, v64, v2 dst_sel:DWORD dst_unused:UNUSED_PAD src0_sel:DWORD src1_sel:WORD_1
	global_load_lds_dwordx4 v[30:31], off
	v_lshl_add_u64 v[30:31], s[18:19], 0, v[42:43]
	v_lshl_add_u64 v[30:31], v[30:31], 0, v[50:51]
	s_mov_b32 m0, s49
	v_lshlrev_b32_e32 v2, 9, v3
	global_load_lds_dwordx4 v[30:31], off
	v_lshl_add_u64 v[30:31], s[22:23], 0, v[42:43]
	v_lshl_add_u64 v[30:31], v[30:31], 0, v[52:53]
	s_mov_b32 m0, s50
	v_and_b32_e32 v42, 0x1fffe00, v2
	global_load_lds_dwordx4 v[30:31], off
	v_lshl_add_u64 v[30:31], s[18:19], 0, v[42:43]
	v_lshl_add_u64 v[30:31], v[30:31], 0, v[48:49]
	s_mov_b32 m0, s51
	v_mfma_f32_16x16x32_bf16 v[22:25], v[162:165], v[186:189], v[22:25]
	global_load_lds_dwordx4 v[30:31], off
	v_lshl_add_u64 v[30:31], s[22:23], 0, v[42:43]
	v_lshlrev_b32_sdwa v42, v64, v3 dst_sel:DWORD dst_unused:UNUSED_PAD src0_sel:DWORD src1_sel:WORD_1
	v_lshl_add_u64 v[30:31], v[30:31], 0, v[52:53]
	s_mov_b32 m0, s52
	v_lshl_add_u64 v[2:3], s[18:19], 0, v[42:43]
	global_load_lds_dwordx4 v[30:31], off
	v_lshl_add_u64 v[2:3], v[2:3], 0, v[46:47]
	s_mov_b32 m0, s53
	v_mfma_f32_16x16x32_bf16 v[170:173], v[162:165], v[182:185], v[170:173]
	global_load_lds_dwordx4 v[2:3], off
	v_lshl_add_u64 v[2:3], s[22:23], 0, v[42:43]
	v_lshl_add_u64 v[2:3], v[2:3], 0, v[52:53]
	s_mov_b32 m0, s54
	v_mfma_f32_16x16x32_bf16 v[166:169], v[162:165], v[178:181], v[166:169]
	global_load_lds_dwordx4 v[2:3], off
	s_waitcnt vmcnt(8)
	ds_read_b128 v[178:181], v145 offset:8192
	ds_read_b128 v[182:185], v149 offset:8192
	ds_read_b128 v[186:189], v151 offset:8192
	ds_read_b128 v[190:193], v153 offset:8192
	v_add_f32_e32 v2, v41, v57
	v_add_f32_e32 v2, v40, v2
	v_add_f32_e32 v3, v59, v155
	v_mfma_f32_16x16x32_bf16 v[36:39], v[162:165], v[174:177], v[36:39]
	v_add_f32_e32 v2, v3, v2
	v_add_f32_e32 v3, v156, v157
	v_add_f32_e32 v2, v3, v2
	v_add_f32_e32 v3, v158, v160
	v_add_f32_e32 v30, v3, v2
	s_waitcnt lgkmcnt(0)
	v_mfma_f32_16x16x32_bf16 v[162:165], v[178:181], v[10:13], 0
	v_cmp_ge_i32_e32 vcc, s13, v105
	s_mov_b32 m0, s44
	v_mfma_f32_16x16x32_bf16 v[174:177], v[186:189], v[10:13], 0
	v_mfma_f32_16x16x32_bf16 v[162:165], v[182:185], v[6:9], v[162:165]
	v_mfma_f32_16x16x32_bf16 v[174:177], v[190:193], v[6:9], v[174:177]
	s_nop 6
	v_mul_f32_e32 v2, 0x3fb8aa3b, v162
	v_exp_f32_e32 v2, v2
	v_mul_f32_e32 v3, 0x3fb8aa3b, v174
	v_exp_f32_e32 v3, v3
	v_cndmask_b32_e32 v31, 0, v2, vcc
	v_mul_f32_e32 v2, 0x3fb8aa3b, v163
	v_cmp_ge_i32_e32 vcc, s13, v106
	v_exp_f32_e32 v2, v2
	s_nop 0
	v_cndmask_b32_e32 v40, 0, v3, vcc
	v_mul_f32_e32 v3, 0x3fb8aa3b, v175
	v_exp_f32_e32 v3, v3
	v_cmp_ge_i32_e32 vcc, s13, v107
	s_nop 1
	v_cndmask_b32_e32 v41, 0, v2, vcc
	v_mul_f32_e32 v2, 0x3fb8aa3b, v164
	v_cmp_ge_i32_e32 vcc, s13, v108
	v_exp_f32_e32 v2, v2
	v_cvt_pk_bf16_f32 v162, v31, v41
	s_nop 0
	v_cndmask_b32_e32 v57, 0, v3, vcc
	v_mul_f32_e32 v3, 0x3fb8aa3b, v176
	v_exp_f32_e32 v3, v3
	v_cmp_ge_i32_e32 vcc, s13, v109
	s_nop 1
	v_cndmask_b32_e32 v59, 0, v2, vcc
	v_mul_f32_e32 v2, 0x3fb8aa3b, v165
	v_cmp_ge_i32_e32 vcc, s13, v110
	v_exp_f32_e32 v2, v2
	s_nop 0
	v_cndmask_b32_e32 v155, 0, v3, vcc
	v_mul_f32_e32 v3, 0x3fb8aa3b, v177
	v_exp_f32_e32 v3, v3
	v_cmp_ge_i32_e32 vcc, s13, v111
	s_nop 1
	v_cndmask_b32_e32 v156, 0, v2, vcc
	v_lshlrev_b32_e32 v2, 9, v4
	v_cmp_ge_i32_e32 vcc, s13, v112
	v_and_b32_e32 v42, 0x1fffe00, v2
	v_cvt_pk_bf16_f32 v163, v59, v156
	v_cvt_pk_bf16_f32 v164, v40, v57
	s_nop 0
	v_cndmask_b32_e32 v157, 0, v3, vcc
	v_lshl_add_u64 v[2:3], s[18:19], 0, v[42:43]
	v_cvt_pk_bf16_f32 v165, v155, v157
	ds_read_b64_tr_b16 v[186:187], v89
	ds_read_b64_tr_b16 v[188:189], v90
	ds_read_b64_tr_b16 v[182:183], v91
	ds_read_b64_tr_b16 v[184:185], v92
	ds_read_b64_tr_b16 v[178:179], v93
	ds_read_b64_tr_b16 v[180:181], v94
	ds_read_b64_tr_b16 v[174:175], v95
	ds_read_b64_tr_b16 v[176:177], v96
	s_waitcnt lgkmcnt(0)
	v_lshl_add_u64 v[2:3], v[2:3], 0, v[44:45]
	ds_write_b64 v29, v[26:27]
	global_load_lds_dwordx4 v[2:3], off
	v_lshl_add_u64 v[2:3], s[22:23], 0, v[42:43]
	v_lshl_add_u64 v[2:3], v[2:3], 0, v[52:53]
	s_mov_b32 m0, s58
	v_lshlrev_b32_sdwa v42, v64, v4 dst_sel:DWORD dst_unused:UNUSED_PAD src0_sel:DWORD src1_sel:WORD_1
	global_load_lds_dwordx4 v[2:3], off
	v_lshl_add_u64 v[2:3], s[18:19], 0, v[42:43]
	v_lshl_add_u64 v[2:3], v[2:3], 0, v[50:51]
	s_mov_b32 m0, s59
	v_mfma_f32_16x16x32_bf16 v[166:169], v[162:165], v[178:181], v[166:169]
	global_load_lds_dwordx4 v[2:3], off
	v_lshl_add_u64 v[2:3], s[22:23], 0, v[42:43]
	v_lshl_add_u64 v[2:3], v[2:3], 0, v[52:53]
	s_mov_b32 m0, s60
	v_add_f32_e32 v27, v41, v57
	global_load_lds_dwordx4 v[2:3], off
	v_lshlrev_b32_e32 v2, 9, v5
	v_and_b32_e32 v42, 0x1fffe00, v2
	v_lshl_add_u64 v[2:3], s[18:19], 0, v[42:43]
	v_lshl_add_u64 v[2:3], v[2:3], 0, v[48:49]
	s_mov_b32 m0, s61
	v_mfma_f32_16x16x32_bf16 v[36:39], v[162:165], v[174:177], v[36:39]
	global_load_lds_dwordx4 v[2:3], off
	v_lshl_add_u64 v[2:3], s[22:23], 0, v[42:43]
	v_lshl_add_u64 v[2:3], v[2:3], 0, v[52:53]
	s_mov_b32 m0, s64
	v_lshlrev_b32_sdwa v42, v64, v5 dst_sel:DWORD dst_unused:UNUSED_PAD src0_sel:DWORD src1_sel:WORD_1
	global_load_lds_dwordx4 v[2:3], off
	v_lshl_add_u64 v[2:3], s[18:19], 0, v[42:43]
	v_lshl_add_u64 v[2:3], v[2:3], 0, v[46:47]
	s_mov_b32 m0, s65
	s_nop 0
	global_load_lds_dwordx4 v[2:3], off
	v_lshl_add_u64 v[2:3], s[22:23], 0, v[42:43]
	v_lshl_add_u64 v[2:3], v[2:3], 0, v[52:53]
	s_mov_b32 m0, s66
	s_nop 0
	global_load_lds_dwordx4 v[2:3], off
	v_mfma_f32_16x16x32_bf16 v[2:5], v[162:165], v[186:189], v[22:25]
	s_waitcnt vmcnt(8)
	s_nop 2
	v_add_f32_e32 v22, v31, v40
	v_add_f32_e32 v26, v30, v22
	v_mfma_f32_16x16x32_bf16 v[22:25], v[162:165], v[182:185], v[170:173]
	s_nop 2
	ds_read_b128 v[170:173], v145
	ds_read_b128 v[178:181], v149
	ds_read_b128 v[182:185], v151
	ds_read_b128 v[186:189], v153
	v_add_f32_e32 v26, v27, v26
	v_add_f32_e32 v27, v59, v155
	v_add_f32_e32 v26, v27, v26
	v_add_f32_e32 v27, v156, v157
	v_add_f32_e32 v29, v27, v26
	s_waitcnt lgkmcnt(0)
	v_mfma_f32_16x16x32_bf16 v[162:165], v[170:173], v[10:13], 0
	v_cmp_ge_i32_e32 vcc, s13, v113
	s_mov_b32 m0, s46
	v_mfma_f32_16x16x32_bf16 v[170:173], v[182:185], v[10:13], 0
	v_mfma_f32_16x16x32_bf16 v[162:165], v[178:181], v[6:9], v[162:165]
	v_mfma_f32_16x16x32_bf16 v[170:173], v[186:189], v[6:9], v[170:173]
	s_nop 6
	v_mul_f32_e32 v26, 0x3fb8aa3b, v162
	v_exp_f32_e32 v26, v26
	v_mul_f32_e32 v27, 0x3fb8aa3b, v170
	v_exp_f32_e32 v27, v27
	v_cndmask_b32_e32 v30, 0, v26, vcc
	v_mul_f32_e32 v26, 0x3fb8aa3b, v163
	v_cmp_ge_i32_e32 vcc, s13, v114
	v_exp_f32_e32 v26, v26
	s_nop 0
	v_cndmask_b32_e32 v31, 0, v27, vcc
	v_mul_f32_e32 v27, 0x3fb8aa3b, v171
	v_exp_f32_e32 v27, v27
	v_cmp_ge_i32_e32 vcc, s13, v115
	s_nop 1
	v_cndmask_b32_e32 v40, 0, v26, vcc
	v_mul_f32_e32 v26, 0x3fb8aa3b, v164
	v_cmp_ge_i32_e32 vcc, s13, v116
	v_exp_f32_e32 v26, v26
	v_cvt_pk_bf16_f32 v162, v30, v40
	s_nop 0
	v_cndmask_b32_e32 v41, 0, v27, vcc
	v_mul_f32_e32 v27, 0x3fb8aa3b, v172
	v_exp_f32_e32 v27, v27
	v_cmp_ge_i32_e32 vcc, s13, v117
	s_nop 1
	v_cndmask_b32_e32 v57, 0, v26, vcc
	v_mul_f32_e32 v26, 0x3fb8aa3b, v165
	v_cmp_ge_i32_e32 vcc, s13, v118
	v_exp_f32_e32 v26, v26
	s_nop 0
	v_cndmask_b32_e32 v59, 0, v27, vcc
	v_mul_f32_e32 v27, 0x3fb8aa3b, v173
	v_exp_f32_e32 v27, v27
	v_cmp_ge_i32_e32 vcc, s13, v119
	s_nop 1
	v_cndmask_b32_e32 v155, 0, v26, vcc
	v_lshlrev_b32_e32 v26, 9, v32
	v_cmp_ge_i32_e32 vcc, s13, v120
	v_and_b32_e32 v42, 0x1fffe00, v26
	v_cvt_pk_bf16_f32 v163, v57, v155
	v_cvt_pk_bf16_f32 v164, v31, v41
	s_nop 0
	v_cndmask_b32_e32 v156, 0, v27, vcc
	v_lshl_add_u64 v[26:27], s[18:19], 0, v[42:43]
	v_cvt_pk_bf16_f32 v165, v59, v156
	ds_read_b64_tr_b16 v[182:183], v73
	ds_read_b64_tr_b16 v[184:185], v74
	ds_read_b64_tr_b16 v[178:179], v75
	ds_read_b64_tr_b16 v[180:181], v76
	ds_read_b64_tr_b16 v[174:175], v77
	ds_read_b64_tr_b16 v[176:177], v78
	ds_read_b64_tr_b16 v[170:171], v79
	ds_read_b64_tr_b16 v[172:173], v80
	s_waitcnt lgkmcnt(0)
	v_lshl_add_u64 v[26:27], v[26:27], 0, v[44:45]
	global_load_lds_dwordx4 v[26:27], off
	v_lshl_add_u64 v[26:27], s[22:23], 0, v[42:43]
	v_lshl_add_u64 v[26:27], v[26:27], 0, v[52:53]
	s_mov_b32 m0, s48
	v_lshlrev_b32_sdwa v42, v64, v32 dst_sel:DWORD dst_unused:UNUSED_PAD src0_sel:DWORD src1_sel:WORD_1
	global_load_lds_dwordx4 v[26:27], off
	v_lshl_add_u64 v[26:27], s[18:19], 0, v[42:43]
	v_lshl_add_u64 v[26:27], v[26:27], 0, v[50:51]
	s_mov_b32 m0, s49
	v_mfma_f32_16x16x32_bf16 v[182:185], v[162:165], v[182:185], v[2:5]
	global_load_lds_dwordx4 v[26:27], off
	v_lshl_add_u64 v[26:27], s[22:23], 0, v[42:43]
	v_lshl_add_u64 v[26:27], v[26:27], 0, v[52:53]
	s_mov_b32 m0, s50
	v_add_f32_e32 v2, v30, v31
	global_load_lds_dwordx4 v[26:27], off
	v_lshlrev_b32_e32 v26, 9, v33
	v_and_b32_e32 v42, 0x1fffe00, v26
	v_lshl_add_u64 v[26:27], s[18:19], 0, v[42:43]
	v_lshl_add_u64 v[26:27], v[26:27], 0, v[48:49]
	s_mov_b32 m0, s51
	v_add_f32_e32 v2, v29, v2
	global_load_lds_dwordx4 v[26:27], off
	v_lshl_add_u64 v[26:27], s[22:23], 0, v[42:43]
	v_lshl_add_u64 v[26:27], v[26:27], 0, v[52:53]
	s_mov_b32 m0, s52
	v_lshlrev_b32_sdwa v42, v64, v33 dst_sel:DWORD dst_unused:UNUSED_PAD src0_sel:DWORD src1_sel:WORD_1
	global_load_lds_dwordx4 v[26:27], off
	v_lshl_add_u64 v[26:27], s[18:19], 0, v[42:43]
	v_lshl_add_u64 v[26:27], v[26:27], 0, v[46:47]
	s_mov_b32 m0, s53
	v_add_f32_e32 v3, v40, v41
	global_load_lds_dwordx4 v[26:27], off
	v_lshl_add_u64 v[26:27], s[22:23], 0, v[42:43]
	v_lshl_add_u64 v[26:27], v[26:27], 0, v[52:53]
	s_mov_b32 m0, s54
	v_add_f32_e32 v2, v3, v2
	global_load_lds_dwordx4 v[26:27], off
	v_add_f32_e32 v3, v57, v59
	s_waitcnt vmcnt(8)
	v_mfma_f32_16x16x32_bf16 v[178:181], v[162:165], v[178:181], v[22:25]
	v_add_f32_e32 v26, v3, v2
	v_add_f32_e32 v27, v155, v156
	v_add_f32_e32 v57, v27, v26
	v_mfma_f32_16x16x32_bf16 v[166:169], v[162:165], v[174:177], v[166:169]
	ds_read_b128 v[2:5], v145 offset:8192
	ds_read_b128 v[22:25], v149 offset:8192
	ds_read_b128 v[30:33], v151 offset:8192
	ds_read_b128 v[174:177], v153 offset:8192
	v_mfma_f32_16x16x32_bf16 v[36:39], v[162:165], v[170:173], v[36:39]
	s_waitcnt lgkmcnt(0)
	v_mfma_f32_16x16x32_bf16 v[2:5], v[2:5], v[10:13], 0
	v_cmp_ge_i32_e32 vcc, s13, v121
	v_lshlrev_b32_e32 v40, 9, v34
	v_and_b32_e32 v42, 0x1fffe00, v40
	v_mfma_f32_16x16x32_bf16 v[2:5], v[22:25], v[6:9], v[2:5]
	v_lshl_add_u64 v[40:41], s[18:19], 0, v[42:43]
	s_mov_b32 m0, s44
	v_lshl_add_u64 v[40:41], v[40:41], 0, v[44:45]
	v_mfma_f32_16x16x32_bf16 v[22:25], v[30:33], v[10:13], 0
	v_mfma_f32_16x16x32_bf16 v[22:25], v[174:177], v[6:9], v[22:25]
	s_nop 2
	v_mul_f32_e32 v2, 0x3fb8aa3b, v2
	v_exp_f32_e32 v2, v2
	s_nop 0
	v_cndmask_b32_e32 v59, 0, v2, vcc
	v_mul_f32_e32 v2, 0x3fb8aa3b, v3
	v_mul_f32_e32 v22, 0x3fb8aa3b, v22
	v_exp_f32_e32 v22, v22
	v_exp_f32_e32 v2, v2
	v_mul_f32_e32 v3, 0x3fb8aa3b, v23
	v_exp_f32_e32 v3, v3
	v_cmp_ge_i32_e32 vcc, s13, v122
	s_nop 1
	v_cndmask_b32_e32 v155, 0, v22, vcc
	v_cmp_ge_i32_e32 vcc, s13, v123
	s_nop 1
	v_cndmask_b32_e32 v156, 0, v2, vcc
	v_cmp_ge_i32_e32 vcc, s13, v124
	v_mul_f32_e32 v2, 0x3fb8aa3b, v4
	v_exp_f32_e32 v2, v2
	v_cndmask_b32_e32 v157, 0, v3, vcc
	v_mul_f32_e32 v3, 0x3fb8aa3b, v24
	v_exp_f32_e32 v3, v3
	v_cmp_ge_i32_e32 vcc, s13, v125
	v_cvt_pk_bf16_f32 v162, v59, v156
	s_nop 1
	v_cndmask_b32_e32 v158, 0, v2, vcc
	v_cmp_ge_i32_e32 vcc, s13, v126
	v_mul_f32_e32 v2, 0x3fb8aa3b, v5
	v_exp_f32_e32 v2, v2
	v_cndmask_b32_e32 v160, 0, v3, vcc
	v_mul_f32_e32 v3, 0x3fb8aa3b, v25
	v_exp_f32_e32 v3, v3
	v_cmp_ge_i32_e32 vcc, s13, v127
	s_nop 1
	v_cndmask_b32_e32 v198, 0, v2, vcc
	v_cmp_ge_i32_e32 vcc, s13, v128
	v_cvt_pk_bf16_f32 v163, v158, v198
	v_cvt_pk_bf16_f32 v164, v155, v157
	s_nop 1
	v_cndmask_b32_e32 v199, 0, v3, vcc
	v_cvt_pk_bf16_f32 v165, v160, v199
	ds_read_b64_tr_b16 v[190:191], v89
	ds_read_b64_tr_b16 v[192:193], v90
	ds_read_b64_tr_b16 v[186:187], v91
	ds_read_b64_tr_b16 v[188:189], v92
	ds_read_b64_tr_b16 v[174:175], v93
	ds_read_b64_tr_b16 v[176:177], v94
	ds_read_b64_tr_b16 v[170:171], v95
	ds_read_b64_tr_b16 v[172:173], v96
	s_waitcnt lgkmcnt(0)
	s_waitcnt lgkmcnt(0)
	ds_read_b128 v[30:33], v28
	ds_read_b128 v[22:25], v28 offset:16
	ds_read_b128 v[2:5], v28 offset:32
	ds_read_b128 v[26:29], v28 offset:48
	global_load_lds_dwordx4 v[40:41], off
	v_lshl_add_u64 v[40:41], s[22:23], 0, v[42:43]
	v_lshl_add_u64 v[40:41], v[40:41], 0, v[52:53]
	s_mov_b32 m0, s58
	v_lshlrev_b32_sdwa v42, v64, v34 dst_sel:DWORD dst_unused:UNUSED_PAD src0_sel:DWORD src1_sel:WORD_1
	global_load_lds_dwordx4 v[40:41], off
	v_lshl_add_u64 v[40:41], s[18:19], 0, v[42:43]
	v_lshl_add_u64 v[40:41], v[40:41], 0, v[50:51]
	s_mov_b32 m0, s59
	v_lshlrev_b32_e32 v34, 9, v35
	global_load_lds_dwordx4 v[40:41], off
	v_lshl_add_u64 v[40:41], s[22:23], 0, v[42:43]
	v_lshl_add_u64 v[40:41], v[40:41], 0, v[52:53]
	s_mov_b32 m0, s60
	v_and_b32_e32 v42, 0x1fffe00, v34
	global_load_lds_dwordx4 v[40:41], off
	v_lshl_add_u64 v[40:41], s[18:19], 0, v[42:43]
	v_lshl_add_u64 v[40:41], v[40:41], 0, v[48:49]
	s_mov_b32 m0, s61
	v_mfma_f32_16x16x32_bf16 v[182:185], v[162:165], v[190:193], v[182:185]
	global_load_lds_dwordx4 v[40:41], off
	v_lshl_add_u64 v[40:41], s[22:23], 0, v[42:43]
	v_lshlrev_b32_sdwa v42, v64, v35 dst_sel:DWORD dst_unused:UNUSED_PAD src0_sel:DWORD src1_sel:WORD_1
	v_lshl_add_u64 v[40:41], v[40:41], 0, v[52:53]
	s_mov_b32 m0, s64
	v_lshl_add_u64 v[34:35], s[18:19], 0, v[42:43]
	global_load_lds_dwordx4 v[40:41], off
	v_lshl_add_u64 v[34:35], v[34:35], 0, v[46:47]
	s_mov_b32 m0, s65
	v_mfma_f32_16x16x32_bf16 v[178:181], v[162:165], v[186:189], v[178:181]
	global_load_lds_dwordx4 v[34:35], off
	v_lshl_add_u64 v[34:35], s[22:23], 0, v[42:43]
	v_lshl_add_u64 v[34:35], v[34:35], 0, v[52:53]
	s_mov_b32 m0, s66
	v_mfma_f32_16x16x32_bf16 v[166:169], v[162:165], v[174:177], v[166:169]
	global_load_lds_dwordx4 v[34:35], off
	s_waitcnt vmcnt(8)
	v_add_f32_e32 v34, v59, v155
	ds_read_b128 v[174:177], v145
	ds_read_b128 v[186:189], v149
	ds_read_b128 v[190:193], v151
	ds_read_b128 v[194:197], v153
	v_add_f32_e32 v34, v57, v34
	v_add_f32_e32 v35, v156, v157
	v_add_f32_e32 v34, v35, v34
	v_add_f32_e32 v35, v158, v160
	v_add_f32_e32 v40, v35, v34
	v_mfma_f32_16x16x32_bf16 v[34:37], v[162:165], v[170:173], v[36:39]
	s_nop 2
	v_add_f32_e32 v38, v198, v199
	v_add_f32_e32 v57, v38, v40
	s_waitcnt lgkmcnt(0)
	v_mfma_f32_16x16x32_bf16 v[38:41], v[174:177], v[10:13], 0
	v_cmp_ge_i32_e32 vcc, s13, v129
	s_mov_b32 m0, s46
	v_mfma_f32_16x16x32_bf16 v[38:41], v[186:189], v[6:9], v[38:41]
	v_mfma_f32_16x16x32_bf16 v[162:165], v[190:193], v[10:13], 0
	v_mfma_f32_16x16x32_bf16 v[162:165], v[194:197], v[6:9], v[162:165]
	s_nop 5
	v_mul_f32_e32 v38, 0x3fb8aa3b, v38
	v_exp_f32_e32 v38, v38
	s_nop 0
	v_cndmask_b32_e32 v59, 0, v38, vcc
	v_mul_f32_e32 v38, 0x3fb8aa3b, v39
	v_mul_f32_e32 v42, 0x3fb8aa3b, v162
	v_exp_f32_e32 v42, v42
	v_exp_f32_e32 v38, v38
	v_mul_f32_e32 v39, 0x3fb8aa3b, v163
	v_exp_f32_e32 v39, v39
	v_cmp_ge_i32_e32 vcc, s13, v130
	s_nop 1
	v_cndmask_b32_e32 v155, 0, v42, vcc
	v_cmp_ge_i32_e32 vcc, s13, v131
	v_lshlrev_b32_e32 v42, 9, v30
	v_and_b32_e32 v42, 0x1fffe00, v42
	v_cndmask_b32_e32 v158, 0, v38, vcc
	v_cmp_ge_i32_e32 vcc, s13, v132
	v_mul_f32_e32 v38, 0x3fb8aa3b, v40
	v_exp_f32_e32 v38, v38
	v_cndmask_b32_e32 v160, 0, v39, vcc
	v_mul_f32_e32 v39, 0x3fb8aa3b, v164
	v_exp_f32_e32 v39, v39
	v_cmp_ge_i32_e32 vcc, s13, v133
	v_lshl_add_u64 v[156:157], s[14:15], 0, v[42:43]
	v_lshl_add_u64 v[156:157], v[156:157], 0, v[44:45]
	v_cndmask_b32_e32 v190, 0, v38, vcc
	v_cmp_ge_i32_e32 vcc, s13, v134
	v_mul_f32_e32 v38, 0x3fb8aa3b, v41
	v_exp_f32_e32 v38, v38
	v_cndmask_b32_e32 v191, 0, v39, vcc
	v_mul_f32_e32 v39, 0x3fb8aa3b, v165
	v_exp_f32_e32 v39, v39
	v_cmp_ge_i32_e32 vcc, s13, v135
	s_nop 1
	v_cndmask_b32_e32 v194, 0, v38, vcc
	v_cmp_ge_i32_e32 vcc, s13, v136
	v_cvt_pk_bf16_f32 v38, v59, v158
	s_nop 1
	v_cndmask_b32_e32 v195, 0, v39, vcc
	v_cvt_pk_bf16_f32 v39, v190, v194
	v_cvt_pk_bf16_f32 v40, v155, v160
	v_cvt_pk_bf16_f32 v41, v191, v195
	ds_read_b64_tr_b16 v[186:187], v73
	ds_read_b64_tr_b16 v[188:189], v74
	ds_read_b64_tr_b16 v[174:175], v75
	ds_read_b64_tr_b16 v[176:177], v76
	ds_read_b64_tr_b16 v[170:171], v77
	ds_read_b64_tr_b16 v[172:173], v78
	ds_read_b64_tr_b16 v[162:163], v79
	ds_read_b64_tr_b16 v[164:165], v80
	s_waitcnt lgkmcnt(0)
	global_load_lds_dwordx4 v[156:157], off
	v_lshl_add_u64 v[156:157], s[16:17], 0, v[42:43]
	v_lshl_add_u64 v[156:157], v[156:157], 0, v[52:53]
	s_mov_b32 m0, s48
	v_lshlrev_b32_sdwa v42, v64, v30 dst_sel:DWORD dst_unused:UNUSED_PAD src0_sel:DWORD src1_sel:WORD_1
	global_load_lds_dwordx4 v[156:157], off
	v_lshl_add_u64 v[156:157], s[14:15], 0, v[42:43]
	v_lshl_add_u64 v[156:157], v[156:157], 0, v[50:51]
	s_mov_b32 m0, s49
	v_lshlrev_b32_e32 v30, 9, v31
	global_load_lds_dwordx4 v[156:157], off
	v_lshl_add_u64 v[156:157], s[16:17], 0, v[42:43]
	v_lshl_add_u64 v[156:157], v[156:157], 0, v[52:53]
	s_mov_b32 m0, s50
	v_and_b32_e32 v42, 0x1fffe00, v30
	global_load_lds_dwordx4 v[156:157], off
	v_lshl_add_u64 v[156:157], s[14:15], 0, v[42:43]
	v_lshl_add_u64 v[156:157], v[156:157], 0, v[48:49]
	s_mov_b32 m0, s51
	v_mfma_f32_16x16x32_bf16 v[182:185], v[38:41], v[186:189], v[182:185]
	global_load_lds_dwordx4 v[156:157], off
	v_lshl_add_u64 v[156:157], s[16:17], 0, v[42:43]
	v_lshlrev_b32_sdwa v42, v64, v31 dst_sel:DWORD dst_unused:UNUSED_PAD src0_sel:DWORD src1_sel:WORD_1
	v_lshl_add_u64 v[156:157], v[156:157], 0, v[52:53]
	s_mov_b32 m0, s52
	v_lshl_add_u64 v[30:31], s[14:15], 0, v[42:43]
	global_load_lds_dwordx4 v[156:157], off
	v_lshl_add_u64 v[30:31], v[30:31], 0, v[46:47]
	s_mov_b32 m0, s53
	v_mfma_f32_16x16x32_bf16 v[174:177], v[38:41], v[174:177], v[178:181]
	global_load_lds_dwordx4 v[30:31], off
	v_lshl_add_u64 v[30:31], s[16:17], 0, v[42:43]
	v_lshl_add_u64 v[30:31], v[30:31], 0, v[52:53]
	s_mov_b32 m0, s54
	v_mfma_f32_16x16x32_bf16 v[166:169], v[38:41], v[170:173], v[166:169]
	global_load_lds_dwordx4 v[30:31], off
	v_add_f32_e32 v30, v59, v155
	v_add_f32_e32 v30, v57, v30
	v_add_f32_e32 v31, v158, v160
	s_waitcnt vmcnt(8)
	v_add_f32_e32 v30, v31, v30
	v_add_f32_e32 v31, v190, v191
	ds_read_b128 v[170:173], v145 offset:8192
	ds_read_b128 v[178:181], v149 offset:8192
	ds_read_b128 v[186:189], v151 offset:8192
	ds_read_b128 v[190:193], v153 offset:8192
	v_add_f32_e32 v30, v31, v30
	v_add_f32_e32 v31, v194, v195
	v_add_f32_e32 v30, v31, v30
	v_mfma_f32_16x16x32_bf16 v[162:165], v[38:41], v[162:165], v[34:37]
	s_waitcnt lgkmcnt(0)
	v_mfma_f32_16x16x32_bf16 v[34:37], v[170:173], v[10:13], 0
	v_cmp_ge_i32_e32 vcc, s13, v137
	v_mfma_f32_16x16x32_bf16 v[10:13], v[186:189], v[10:13], 0
	v_mfma_f32_16x16x32_bf16 v[34:37], v[178:181], v[6:9], v[34:37]
	v_mfma_f32_16x16x32_bf16 v[6:9], v[190:193], v[6:9], v[10:13]
	s_nop 6
	v_mul_f32_e32 v31, 0x3fb8aa3b, v34
	v_exp_f32_e32 v31, v31
	v_mul_f32_e32 v6, 0x3fb8aa3b, v6
	v_exp_f32_e32 v6, v6
	v_mul_f32_e32 v12, 0x3fb8aa3b, v35
	v_exp_f32_e32 v12, v12
	v_mul_f32_e32 v7, 0x3fb8aa3b, v7
	v_exp_f32_e32 v7, v7
	v_cndmask_b32_e32 v10, 0, v31, vcc
	v_cmp_ge_i32_e32 vcc, s13, v138
	v_mul_f32_e32 v8, 0x3fb8aa3b, v8
	v_exp_f32_e32 v8, v8
	v_cndmask_b32_e32 v11, 0, v6, vcc
	v_cmp_ge_i32_e32 vcc, s13, v139
	v_add_f32_e32 v6, v10, v11
	v_add_f32_e32 v6, v30, v6
	v_cndmask_b32_e32 v12, 0, v12, vcc
	v_cmp_ge_i32_e32 vcc, s13, v140
	s_nop 1
	v_cndmask_b32_e32 v13, 0, v7, vcc
	v_add_f32_e32 v7, v12, v13
	v_add_f32_e32 v6, v7, v6
	v_mul_f32_e32 v7, 0x3fb8aa3b, v36
	v_exp_f32_e32 v7, v7
	v_cmp_ge_i32_e32 vcc, s13, v141
	s_nop 1
	v_cndmask_b32_e32 v7, 0, v7, vcc
	v_cmp_ge_i32_e32 vcc, s13, v142
	s_nop 1
	v_cndmask_b32_e32 v30, 0, v8, vcc
	v_add_f32_e32 v8, v7, v30
	v_add_f32_e32 v31, v8, v6
	v_mul_f32_e32 v6, 0x3fb8aa3b, v37
	v_exp_f32_e32 v6, v6
	v_mul_f32_e32 v8, 0x3fb8aa3b, v9
	v_exp_f32_e32 v8, v8
	v_cmp_ge_i32_e32 vcc, s13, v143
	s_nop 1
	v_cndmask_b32_e32 v42, 0, v6, vcc
	v_cmp_ge_i32_e32 vcc, s13, v144
	v_cvt_pk_bf16_f32 v6, v10, v12
	v_cvt_pk_bf16_f32 v7, v7, v42
	s_nop 1
	v_cndmask_b32_e32 v57, 0, v8, vcc
	v_cvt_pk_bf16_f32 v8, v11, v13
	v_cvt_pk_bf16_f32 v9, v30, v57
	v_add_f32_e32 v30, v42, v57
	v_add_f32_e32 v30, v30, v31
	ds_read_b64_tr_b16 v[10:11], v89
	ds_read_b64_tr_b16 v[12:13], v90
	ds_read_b64_tr_b16 v[38:39], v91
	ds_read_b64_tr_b16 v[40:41], v92
	ds_read_b64_tr_b16 v[34:35], v93
	ds_read_b64_tr_b16 v[36:37], v94
	ds_read_b64_tr_b16 v[170:171], v95
	ds_read_b64_tr_b16 v[172:173], v96
	s_waitcnt lgkmcnt(0)
	s_nop 0
	v_mfma_f32_16x16x32_bf16 v[10:13], v[6:9], v[10:13], v[182:185]
	v_mov_b32_e32 v31, v30
	s_nop 1
	v_permlane16_swap_b32_e32 v30, v31
	v_mfma_f32_16x16x32_bf16 v[38:41], v[6:9], v[38:41], v[174:177]
	v_add_f32_e32 v30, v30, v31
	v_mfma_f32_16x16x32_bf16 v[34:37], v[6:9], v[34:37], v[166:169]
	s_nop 0
	v_mov_b32_e32 v31, v30
	s_nop 1
	v_permlane32_swap_b32_e32 v30, v31
	v_mfma_f32_16x16x32_bf16 v[6:9], v[6:9], v[170:173], v[162:165]
	v_add_f32_e32 v57, v30, v31
	s_nop 0
	v_readlane_b32 s16, v57, 0
	v_readlane_b32 s17, v57, 1
	v_readlane_b32 s18, v57, 2
	v_readlane_b32 s19, v57, 3
	v_mov_b32_e32 v30, s16
	v_mov_b32_e32 v31, s17
	v_mov_b32_e32 v42, s18
	v_mov_b32_e32 v57, s19
	s_and_saveexec_b64 s[14:15], s[6:7]
	s_cbranch_execz .LBB0_977
	s_waitcnt lgkmcnt(0)
	v_div_scale_f32 v59, s[16:17], v57, v57, 1.0
	v_rcp_f32_e32 v155, v59
	s_ashr_i32 s13, s12, 31
	s_lshl_b64 s[10:11], s[10:11], 24
	v_fma_f32 v156, -v59, v155, 1.0
	v_fmac_f32_e32 v155, v156, v155
	v_div_scale_f32 v156, vcc, 1.0, v57, 1.0
	v_mul_f32_e32 v157, v156, v155
	v_fma_f32 v158, -v59, v157, v156
	v_fmac_f32_e32 v157, v158, v155
	v_fma_f32 v59, -v59, v157, v156
	v_div_scale_f32 v156, s[16:17], v42, v42, 1.0
	v_rcp_f32_e32 v158, v156
	v_div_fmas_f32 v59, v59, v155, v157
	v_div_fixup_f32 v57, v59, v57, 1.0
	v_fma_f32 v59, -v156, v158, 1.0
	v_fmac_f32_e32 v158, v59, v158
	v_div_scale_f32 v59, vcc, 1.0, v42, 1.0
	v_mul_f32_e32 v155, v59, v158
	v_fma_f32 v157, -v156, v155, v59
	v_fmac_f32_e32 v155, v157, v158
	v_fma_f32 v59, -v156, v155, v59
	v_div_scale_f32 v156, s[16:17], v31, v31, 1.0
	v_rcp_f32_e32 v157, v156
	v_div_fmas_f32 v59, v59, v158, v155
	v_div_fixup_f32 v42, v59, v42, 1.0
	v_fma_f32 v59, -v156, v157, 1.0
	v_fmac_f32_e32 v157, v59, v157
	v_div_scale_f32 v59, vcc, 1.0, v31, 1.0
	v_mul_f32_e32 v155, v59, v157
	v_fma_f32 v158, -v156, v155, v59
	v_fmac_f32_e32 v155, v158, v157
	v_fma_f32 v59, -v156, v155, v59
	v_div_scale_f32 v156, s[16:17], v30, v30, 1.0
	v_rcp_f32_e32 v158, v156
	v_div_fmas_f32 v59, v59, v157, v155
	v_div_fixup_f32 v155, v59, v31, 1.0
	s_add_u32 s16, s62, s10
	v_fma_f32 v31, -v156, v158, 1.0
	v_fmac_f32_e32 v158, v31, v158
	v_div_scale_f32 v31, vcc, 1.0, v30, 1.0
	v_mul_f32_e32 v59, v31, v158
	v_fma_f32 v157, -v156, v59, v31
	v_fmac_f32_e32 v59, v157, v158
	v_fma_f32 v31, -v156, v59, v31
	v_div_fmas_f32 v31, v31, v158, v59
	s_addc_u32 s17, s63, s11
	s_lshl_b64 s[10:11], s[12:13], 11
	v_div_fixup_f32 v156, v31, v30, 1.0
	s_add_u32 s10, s16, s10
	s_addc_u32 s11, s17, s11
	v_mov_b32_e32 v59, v43
	v_mul_f32_e32 v10, v10, v156
	v_lshl_add_u64 v[30:31], s[10:11], 0, v[58:59]
	v_bfe_u32 v59, v10, 16, 1
	s_lshl_b32 s8, s8, 9
	v_add3_u32 v10, v10, v59, s67
	v_lshl_add_u64 v[30:31], v[30:31], 0, s[8:9]
	global_store_short_d16_hi v[30:31], v10, off
	v_mul_f32_e32 v10, v11, v155
	v_bfe_u32 v11, v10, 16, 1
	v_add3_u32 v10, v10, v11, s67
	global_store_short_d16_hi v[30:31], v10, off offset:128
	v_mul_f32_e32 v10, v12, v42
	v_bfe_u32 v11, v10, 16, 1
	v_add3_u32 v10, v10, v11, s67
	global_store_short_d16_hi v[30:31], v10, off offset:256
	v_mul_f32_e32 v10, v13, v57
	v_bfe_u32 v11, v10, 16, 1
	v_add3_u32 v10, v10, v11, s67
	global_store_short_d16_hi v[30:31], v10, off offset:384
	v_mul_f32_e32 v10, v38, v156
	v_bfe_u32 v11, v10, 16, 1
	v_add3_u32 v10, v10, v11, s67
	global_store_short_d16_hi v[30:31], v10, off offset:32
	v_mul_f32_e32 v10, v39, v155
	v_bfe_u32 v11, v10, 16, 1
	v_add3_u32 v10, v10, v11, s67
	global_store_short_d16_hi v[30:31], v10, off offset:160
	v_mul_f32_e32 v10, v40, v42
	v_bfe_u32 v11, v10, 16, 1
	v_add3_u32 v10, v10, v11, s67
	global_store_short_d16_hi v[30:31], v10, off offset:288
	v_mul_f32_e32 v10, v41, v57
	v_bfe_u32 v11, v10, 16, 1
	v_add3_u32 v10, v10, v11, s67
	global_store_short_d16_hi v[30:31], v10, off offset:416
	v_mul_f32_e32 v10, v34, v156
	v_bfe_u32 v11, v10, 16, 1
	v_add3_u32 v10, v10, v11, s67
	global_store_short_d16_hi v[30:31], v10, off offset:64
	v_mul_f32_e32 v10, v35, v155
	v_bfe_u32 v11, v10, 16, 1
	v_add3_u32 v10, v10, v11, s67
	global_store_short_d16_hi v[30:31], v10, off offset:192
	v_mul_f32_e32 v10, v36, v42
	v_bfe_u32 v11, v10, 16, 1
	v_add3_u32 v10, v10, v11, s67
	global_store_short_d16_hi v[30:31], v10, off offset:320
	v_mul_f32_e32 v10, v37, v57
	v_bfe_u32 v11, v10, 16, 1
	v_add3_u32 v10, v10, v11, s67
	v_mul_f32_e32 v6, v6, v156
	global_store_short_d16_hi v[30:31], v10, off offset:448
	v_bfe_u32 v10, v6, 16, 1
	v_add3_u32 v6, v6, v10, s67
	global_store_short_d16_hi v[30:31], v6, off offset:96
	v_mul_f32_e32 v6, v7, v155
	v_bfe_u32 v7, v6, 16, 1
	v_add3_u32 v6, v6, v7, s67
	global_store_short_d16_hi v[30:31], v6, off offset:224
	v_mul_f32_e32 v6, v8, v42
	v_bfe_u32 v7, v6, 16, 1
	v_add3_u32 v6, v6, v7, s67
	global_store_short_d16_hi v[30:31], v6, off offset:352
	v_mul_f32_e32 v6, v9, v57
	v_bfe_u32 v7, v6, 16, 1
	v_add3_u32 v6, v6, v7, s67
	global_store_short_d16_hi v[30:31], v6, off offset:480
	s_branch .LBB0_977

.LBB0_1032:
	s_or_b64 exec, exec, s[4:5]
	s_add_u32 s12, s28, 0x1c000000
	s_addc_u32 s13, s29, 0
	s_waitcnt lgkmcnt(0)
	v_lshlrev_b32_e32 v1, 1, v212
	s_cmpk_lt_i32 s2, 0x200
	v_readfirstlane_b32 s16, v202
	s_cselect_b64 s[6:7], -1, 0
	s_cmpk_gt_i32 s2, 0x1ff
	v_bitop3_b32 v178, v1, v161, v159 bitop3:0x36
	s_barrier
	s_nop 0
	s_nop 0
	s_nop 0
	s_nop 0
	s_nop 0
	s_nop 0
	s_nop 0
	s_nop 0
	s_cbranch_scc1 .LBB0_1056
	s_ashr_i32 s37, s2, 31
	s_lshr_b32 s4, s37, 29
	s_add_i32 s8, s2, s4
	s_and_b32 s4, s8, -8
	s_sub_i32 s10, s2, s4
	s_cmp_gt_i32 s10, -1
	s_cbranch_scc0 .LBB0_1035
	s_lshl_b32 s9, s10, 6
	s_cbranch_execz .LBB0_1036
	s_branch .LBB0_1037
